# baseline (speedup 1.0000x reference)
; template <int DH, int MODE>
; __device__ void attn_item(const Params& p, int layer, int b, int blk, int head, char* smem) {
;     ...
;       if (MODE == 0) {
;         const int kjb = kj0 + half * 32;
;         float tmax = -1e30f;
; #pragma unroll
;         for (int c = 0; c < 8; ++c) {
;           float4 v = s4[c];
;           float e[4] = {v.x, v.y, v.z, v.w};
; #pragma unroll
;           for (int k = 0; k < 4; ++k) {
;             int kj = kjb + c * 4 + k;
;             bool valid = (kj > row) && (kj <= row + 128);
;             tmax = valid ? fmaxf(tmax, e[k]) : tmax;
;           }
;         }
;         tmax = fmaxf(tmax, __shfl_xor(tmax, 1));
.LBB0_166:
	s_or_b64 exec, exec, s[6:7]
	s_add_i32 s86, s86, 1
	s_min_i32 s6, s86, s84
	s_add_i32 s6, s6, s83
	s_lshl_b32 s6, s6, 6
	s_add_i32 s6, s6, s85
	s_ashr_i32 s7, s6, 31
	s_add_u32 s6, s6, s81
	s_addc_u32 s7, s7, 0
	s_waitcnt lgkmcnt(0)
	s_barrier
	ds_write_b16 v96, v48
	ds_write_b16_d16_hi v96, v48 offset:64
	ds_write_b16 v96, v49 offset:128
	ds_write_b16_d16_hi v96, v49 offset:192
	ds_write_b16 v96, v50 offset:256
	ds_write_b16_d16_hi v96, v50 offset:320
	ds_write_b16 v96, v51 offset:384
	ds_write_b16_d16_hi v96, v51 offset:448
	s_waitcnt vmcnt(0)
	ds_write_b16 v96, v52 offset:2048
	ds_write_b16_d16_hi v96, v52 offset:2112
	ds_write_b16 v96, v53 offset:2176
	ds_write_b16_d16_hi v96, v53 offset:2240
	ds_write_b16 v96, v54 offset:2304
	ds_write_b16_d16_hi v96, v54 offset:2368
	ds_write_b16 v96, v55 offset:2432
	ds_write_b16_d16_hi v96, v55 offset:2496
	v_lshl_add_u64 v[48:49], s[6:7], 0, v[66:67]
	v_mad_u64_u32 v[52:53], s[10:11], v48, s55, v[76:77]
	v_or_b32_e32 v48, s6, v72
	v_mad_i32_i24 v53, v49, s55, v53
	v_mad_u64_u32 v[54:55], s[10:11], v48, s55, v[78:79]
	v_add_co_u32_e32 v48, vcc, 0x4c000, v52
	v_mad_i32_i24 v55, s7, v160, v55
	s_nop 0
	v_addc_co_u32_e32 v49, vcc, 0, v53, vcc
	global_load_dwordx4 v[60:63], v[48:49], off
	s_nop 0
	global_load_dwordx4 v[48:51], v[54:55], off
	global_load_dwordx4 v[56:59], v[52:53], off
	s_nop 0
	global_load_dwordx4 v[52:55], v[54:55], off offset:64
	s_and_saveexec_b64 s[52:53], s[50:51]
	s_cbranch_execz .LBB0_188
	v_or_b32_e32 v101, s8, v89
	s_setprio 1
	s_movk_i32 s91, 0x80
	ds_read_b128 v[164:167], v90 offset:16384
	ds_read_b128 v[168:171], v90 offset:16400
	ds_read_b128 v[172:175], v90 offset:16416
	ds_read_b128 v[176:179], v90 offset:16432
	ds_read_b128 v[180:183], v90 offset:16448
	ds_read_b128 v[184:187], v90 offset:16464
	ds_read_b128 v[188:191], v90 offset:16480
	ds_read_b128 v[192:195], v90 offset:16496
	v_sub_u32_e32 v102, v80, v101
	v_mov_b32_e32 v83, 0xf149f2ca
	v_add_u32_e32 v103, -31, v102
	v_cmp_gt_u32_e32 vcc, 0x61, v103
	s_cmp_eq_u64 vcc, exec
	s_cbranch_scc1 .Lswa_tfast_3
	v_mov_b32_e32 v161, v102
	v_add_u32_e32 v162, -1, v102
	v_add_u32_e32 v163, -2, v102
	v_cmp_gt_u32_e32 vcc, s91, v161
	v_cmp_gt_u32_e64 s[92:93], s91, v162
	v_cmp_gt_u32_e64 s[94:95], s91, v163
	s_waitcnt lgkmcnt(7)
	v_cndmask_b32_e32 v200, v83, v164, vcc
	v_cndmask_b32_e64 v201, v83, v165, s[92:93]
	v_cndmask_b32_e64 v202, v83, v166, s[94:95]
	v_add_u32_e32 v161, -3, v102
	v_add_u32_e32 v162, -4, v102
	v_add_u32_e32 v163, -5, v102
	v_cmp_gt_u32_e32 vcc, s91, v161
	v_cmp_gt_u32_e64 s[92:93], s91, v162
	v_cmp_gt_u32_e64 s[94:95], s91, v163
	s_waitcnt lgkmcnt(6)
	v_cndmask_b32_e32 v203, v83, v167, vcc
	v_cndmask_b32_e64 v204, v83, v168, s[92:93]
	v_cndmask_b32_e64 v205, v83, v169, s[94:95]
	v_add_u32_e32 v161, -6, v102
	v_add_u32_e32 v162, -7, v102
	v_add_u32_e32 v163, -8, v102
	v_cmp_gt_u32_e32 vcc, s91, v161
	v_cmp_gt_u32_e64 s[92:93], s91, v162
	v_cmp_gt_u32_e64 s[94:95], s91, v163
	s_waitcnt lgkmcnt(5)
	v_cndmask_b32_e32 v206, v83, v170, vcc
	v_cndmask_b32_e64 v207, v83, v171, s[92:93]
	v_cndmask_b32_e64 v208, v83, v172, s[94:95]
	v_add_u32_e32 v161, -9, v102
	v_add_u32_e32 v162, -10, v102
	v_add_u32_e32 v163, -11, v102
	v_cmp_gt_u32_e32 vcc, s91, v161
	v_cmp_gt_u32_e64 s[92:93], s91, v162
	v_cmp_gt_u32_e64 s[94:95], s91, v163
	v_cndmask_b32_e32 v209, v83, v173, vcc
	v_cndmask_b32_e64 v210, v83, v174, s[92:93]
	v_cndmask_b32_e64 v211, v83, v175, s[94:95]
	v_add_u32_e32 v161, -12, v102
	v_add_u32_e32 v162, -13, v102
	v_add_u32_e32 v163, -14, v102
	v_cmp_gt_u32_e32 vcc, s91, v161
	v_cmp_gt_u32_e64 s[92:93], s91, v162
	v_cmp_gt_u32_e64 s[94:95], s91, v163
	s_waitcnt lgkmcnt(4)
	v_cndmask_b32_e32 v212, v83, v176, vcc
	v_cndmask_b32_e64 v213, v83, v177, s[92:93]
	v_cndmask_b32_e64 v214, v83, v178, s[94:95]
	v_add_u32_e32 v161, -15, v102
	v_add_u32_e32 v162, -16, v102
	v_add_u32_e32 v163, 0xffffffef, v102
	v_cmp_gt_u32_e32 vcc, s91, v161
	v_cmp_gt_u32_e64 s[92:93], s91, v162
	v_cmp_gt_u32_e64 s[94:95], s91, v163
	s_waitcnt lgkmcnt(3)
	v_cndmask_b32_e32 v215, v83, v179, vcc
	v_cndmask_b32_e64 v216, v83, v180, s[92:93]
	v_cndmask_b32_e64 v217, v83, v181, s[94:95]
	v_add_u32_e32 v161, 0xffffffee, v102
	v_add_u32_e32 v162, 0xffffffed, v102
	v_add_u32_e32 v163, 0xffffffec, v102
	v_cmp_gt_u32_e32 vcc, s91, v161
	v_cmp_gt_u32_e64 s[92:93], s91, v162
	v_cmp_gt_u32_e64 s[94:95], s91, v163
	s_waitcnt lgkmcnt(2)
	v_cndmask_b32_e32 v218, v83, v182, vcc
	v_cndmask_b32_e64 v219, v83, v183, s[92:93]
	v_cndmask_b32_e64 v220, v83, v184, s[94:95]
	v_add_u32_e32 v161, 0xffffffeb, v102
	v_add_u32_e32 v162, 0xffffffea, v102
	v_add_u32_e32 v163, 0xffffffe9, v102
	v_cmp_gt_u32_e32 vcc, s91, v161
	v_cmp_gt_u32_e64 s[92:93], s91, v162
	v_cmp_gt_u32_e64 s[94:95], s91, v163
	v_cndmask_b32_e32 v221, v83, v185, vcc
	v_cndmask_b32_e64 v222, v83, v186, s[92:93]
	v_cndmask_b32_e64 v223, v83, v187, s[94:95]
	v_add_u32_e32 v161, 0xffffffe8, v102
	v_add_u32_e32 v162, 0xffffffe7, v102
	v_add_u32_e32 v163, 0xffffffe6, v102
	v_cmp_gt_u32_e32 vcc, s91, v161
	v_cmp_gt_u32_e64 s[92:93], s91, v162
	v_cmp_gt_u32_e64 s[94:95], s91, v163
	s_waitcnt lgkmcnt(1)
	v_cndmask_b32_e32 v224, v83, v188, vcc
	v_cndmask_b32_e64 v225, v83, v189, s[92:93]
	v_cndmask_b32_e64 v226, v83, v190, s[94:95]
	v_add_u32_e32 v161, 0xffffffe5, v102
	v_add_u32_e32 v162, 0xffffffe4, v102
	v_add_u32_e32 v163, 0xffffffe3, v102
	v_cmp_gt_u32_e32 vcc, s91, v161
	v_cmp_gt_u32_e64 s[92:93], s91, v162
	v_cmp_gt_u32_e64 s[94:95], s91, v163
	s_waitcnt lgkmcnt(0)
	v_cndmask_b32_e32 v227, v83, v191, vcc
	v_cndmask_b32_e64 v228, v83, v192, s[92:93]
	v_cndmask_b32_e64 v229, v83, v193, s[94:95]
	v_add_u32_e32 v161, 0xffffffe2, v102
	v_add_u32_e32 v162, 0xffffffe1, v102
	v_cmp_gt_u32_e32 vcc, s91, v161
	v_cmp_gt_u32_e64 s[92:93], s91, v162
	s_nop 0
	v_cndmask_b32_e32 v230, v83, v194, vcc
	v_cndmask_b32_e64 v231, v83, v195, s[92:93]
	v_max3_f32 v200, v200, v201, v202
	v_max3_f32 v203, v203, v204, v205
	v_max3_f32 v206, v206, v207, v208
	v_max3_f32 v209, v209, v210, v211
	v_max3_f32 v212, v212, v213, v214
	v_max3_f32 v215, v215, v216, v217
	v_max3_f32 v218, v218, v219, v220
	v_max3_f32 v221, v221, v222, v223
	v_max3_f32 v224, v224, v225, v226
	v_max3_f32 v227, v227, v228, v229
	v_max_f32_e32 v230, v230, v231
	v_max3_f32 v200, v200, v203, v206
	v_max3_f32 v209, v209, v212, v215
	v_max3_f32 v218, v218, v221, v224
	v_max_f32_e32 v227, v227, v230
	v_max3_f32 v200, v200, v209, v218
	v_max_f32_e32 v200, v200, v227
	v_mov_b32_e32 v82, v200
	s_branch .Lswa_tdone_3

; template <int DH, int MODE>
; __device__ void attn_item(const Params& p, int layer, int b, int blk, int head, char* smem) {
;     ...
;         tmax = fmaxf(tmax, __shfl_xor(tmax, 1));
;         float m_new = fmaxf(m_run, tmax);
;         float alpha = __builtin_amdgcn_exp2f(m_run - m_new);
;         float psum = 0.f;
; #pragma unroll 2
;         for (int s8 = 0; s8 < 4; ++s8) {
;           float4 va = s4[2 * s8], vb = s4[2 * s8 + 1];
;           float e[8] = {va.x, va.y, va.z, va.w, vb.x, vb.y, vb.z, vb.w};
;           float pv[8];
; #pragma unroll
;           for (int k = 0; k < 8; ++k) {
;             int kj = kjb + s8 * 8 + k;
;             bool valid = (kj > row) && (kj <= row + 128);
;             float pe = valid ? __builtin_amdgcn_exp2f(e[k] - m_new) : 0.f;
;             pv[k] = pe;
;             psum += pe;
.Lswa_tdone_3:
	v_cmp_lt_i32_e32 vcc, v157, v158
	s_mov_b32 s87, 0
	v_mov_b32_e32 v103, 0
	v_cndmask_b32_e32 v83, v156, v157, vcc
	v_lshlrev_b32_e32 v83, 2, v83
	ds_bpermute_b32 v101, v83, v82
	v_mov_b32_e32 v102, v91
	s_waitcnt lgkmcnt(0)
	v_max3_f32 v82, v87, v82, v101
	v_mov_b32_e32 v101, v93
	s_setprio 1
	s_movk_i32 s91, 0x80
	v_sub_u32_e32 v112, v80, v92
	v_add_u32_e32 v113, -31, v112
	v_cmp_gt_u32_e32 vcc, 0x61, v113
	s_cmp_eq_u64 vcc, exec
	s_cbranch_scc1 .Lswa_pfast_3
	v_sub_f32_e32 v164, v164, v82
	v_sub_f32_e32 v165, v165, v82
	v_sub_f32_e32 v166, v166, v82
	v_exp_f32_e32 v164, v164
	v_exp_f32_e32 v165, v165
	v_exp_f32_e32 v166, v166
	v_mov_b32_e32 v196, v112
	v_add_u32_e32 v197, -1, v112
	v_add_u32_e32 v198, -2, v112
	v_cmp_gt_u32_e32 vcc, s91, v196
	v_cmp_gt_u32_e64 s[92:93], s91, v197
	v_cmp_gt_u32_e64 s[94:95], s91, v198
	v_cndmask_b32_e32 v164, 0, v164, vcc
	v_cndmask_b32_e64 v165, 0, v165, s[92:93]
	v_cndmask_b32_e64 v166, 0, v166, s[94:95]
	v_add_f32_e32 v103, v103, v164
	v_add_f32_e32 v103, v103, v165
	v_add_f32_e32 v103, v103, v166
	v_sub_f32_e32 v167, v167, v82
	v_sub_f32_e32 v168, v168, v82
	v_sub_f32_e32 v169, v169, v82
	v_exp_f32_e32 v167, v167
	v_exp_f32_e32 v168, v168
	v_exp_f32_e32 v169, v169
	v_add_u32_e32 v196, -3, v112
	v_add_u32_e32 v197, -4, v112
	v_add_u32_e32 v198, -5, v112
	v_cmp_gt_u32_e32 vcc, s91, v196
	v_cmp_gt_u32_e64 s[92:93], s91, v197
	v_cmp_gt_u32_e64 s[94:95], s91, v198
	v_cndmask_b32_e32 v167, 0, v167, vcc
	v_cndmask_b32_e64 v168, 0, v168, s[92:93]
	v_cndmask_b32_e64 v169, 0, v169, s[94:95]
	v_add_f32_e32 v103, v103, v167
	v_add_f32_e32 v103, v103, v168
	v_add_f32_e32 v103, v103, v169
	v_sub_f32_e32 v170, v170, v82
	v_sub_f32_e32 v171, v171, v82
	v_sub_f32_e32 v172, v172, v82
	v_exp_f32_e32 v170, v170
	v_exp_f32_e32 v171, v171
	v_exp_f32_e32 v172, v172
	v_add_u32_e32 v196, -6, v112
	v_add_u32_e32 v197, -7, v112
	v_add_u32_e32 v198, -8, v112
	v_cmp_gt_u32_e32 vcc, s91, v196
	v_cmp_gt_u32_e64 s[92:93], s91, v197
	v_cmp_gt_u32_e64 s[94:95], s91, v198
	v_cndmask_b32_e32 v170, 0, v170, vcc
	v_cndmask_b32_e64 v171, 0, v171, s[92:93]
	v_cndmask_b32_e64 v172, 0, v172, s[94:95]
	v_add_f32_e32 v103, v103, v170
	v_add_f32_e32 v103, v103, v171
	v_add_f32_e32 v103, v103, v172
	v_sub_f32_e32 v173, v173, v82
	v_sub_f32_e32 v174, v174, v82
	v_sub_f32_e32 v175, v175, v82
	v_exp_f32_e32 v173, v173
	v_exp_f32_e32 v174, v174
	v_exp_f32_e32 v175, v175
	v_add_u32_e32 v196, -9, v112
	v_add_u32_e32 v197, -10, v112
	v_add_u32_e32 v198, -11, v112
	v_cmp_gt_u32_e32 vcc, s91, v196
	v_cmp_gt_u32_e64 s[92:93], s91, v197
	v_cmp_gt_u32_e64 s[94:95], s91, v198
	v_cndmask_b32_e32 v173, 0, v173, vcc
	v_cndmask_b32_e64 v174, 0, v174, s[92:93]
	v_cndmask_b32_e64 v175, 0, v175, s[94:95]
	v_add_f32_e32 v103, v103, v173
	v_add_f32_e32 v103, v103, v174
	v_add_f32_e32 v103, v103, v175
	v_sub_f32_e32 v176, v176, v82
	v_sub_f32_e32 v177, v177, v82
	v_sub_f32_e32 v178, v178, v82
	v_exp_f32_e32 v176, v176
	v_exp_f32_e32 v177, v177
	v_exp_f32_e32 v178, v178
	v_add_u32_e32 v196, -12, v112
	v_add_u32_e32 v197, -13, v112
	v_add_u32_e32 v198, -14, v112
	v_cmp_gt_u32_e32 vcc, s91, v196
	v_cmp_gt_u32_e64 s[92:93], s91, v197
	v_cmp_gt_u32_e64 s[94:95], s91, v198
	v_cndmask_b32_e32 v176, 0, v176, vcc
	v_cndmask_b32_e64 v177, 0, v177, s[92:93]
	v_cndmask_b32_e64 v178, 0, v178, s[94:95]
	v_add_f32_e32 v103, v103, v176
	v_add_f32_e32 v103, v103, v177
	v_add_f32_e32 v103, v103, v178
	v_sub_f32_e32 v179, v179, v82
	v_sub_f32_e32 v180, v180, v82
	v_sub_f32_e32 v181, v181, v82
	v_exp_f32_e32 v179, v179
	v_exp_f32_e32 v180, v180
	v_exp_f32_e32 v181, v181
	v_add_u32_e32 v196, -15, v112
	v_add_u32_e32 v197, -16, v112
	v_add_u32_e32 v198, 0xffffffef, v112
	v_cmp_gt_u32_e32 vcc, s91, v196
	v_cmp_gt_u32_e64 s[92:93], s91, v197
	v_cmp_gt_u32_e64 s[94:95], s91, v198
	v_cndmask_b32_e32 v179, 0, v179, vcc
; __device__ __forceinline__ unsigned pack2(float a, float b) { return (unsigned)f2bf(a) | ((unsigned)f2bf(b) << 16); }
; template <int DH, int MODE>
; __device__ void attn_item(const Params& p, int layer, int b, int blk, int head, char* smem) {
;     ...
; #pragma unroll 2
;         for (int s8 = 0; s8 < 4; ++s8) {
;           float4 va = s4[2 * s8], vb = s4[2 * s8 + 1];
;           float e[8] = {va.x, va.y, va.z, va.w, vb.x, vb.y, vb.z, vb.w};
;           float pv[8];
; #pragma unroll
;           for (int k = 0; k < 8; ++k) {
;             int kj = kjb + s8 * 8 + k;
;             bool valid = (kj > row) && (kj <= row + 128);
;             float pe = valid ? __builtin_amdgcn_exp2f(e[k] - m_new) : 0.f;
;             pv[k] = pe;
;             psum += pe;
;           }
;           uint4 ov;
;           ov.x = pack2(pv[0], pv[1]); ov.y = pack2(pv[2], pv[3]);
;           ov.z = pack2(pv[4], pv[5]); ov.w = pack2(pv[6], pv[7]);
;           *reinterpret_cast<uint4*>(prow + s8 * 16) = ov;
;         }
	v_cndmask_b32_e64 v180, 0, v180, s[92:93]
	v_cndmask_b32_e64 v181, 0, v181, s[94:95]
	v_add_f32_e32 v103, v103, v179
	v_add_f32_e32 v103, v103, v180
	v_add_f32_e32 v103, v103, v181
	v_sub_f32_e32 v182, v182, v82
	v_sub_f32_e32 v183, v183, v82
	v_sub_f32_e32 v184, v184, v82
	v_exp_f32_e32 v182, v182
	v_exp_f32_e32 v183, v183
	v_exp_f32_e32 v184, v184
	v_add_u32_e32 v196, 0xffffffee, v112
	v_add_u32_e32 v197, 0xffffffed, v112
	v_add_u32_e32 v198, 0xffffffec, v112
	v_cmp_gt_u32_e32 vcc, s91, v196
	v_cmp_gt_u32_e64 s[92:93], s91, v197
	v_cmp_gt_u32_e64 s[94:95], s91, v198
	v_cndmask_b32_e32 v182, 0, v182, vcc
	v_cndmask_b32_e64 v183, 0, v183, s[92:93]
	v_cndmask_b32_e64 v184, 0, v184, s[94:95]
	v_add_f32_e32 v103, v103, v182
	v_add_f32_e32 v103, v103, v183
	v_add_f32_e32 v103, v103, v184
	v_sub_f32_e32 v185, v185, v82
	v_sub_f32_e32 v186, v186, v82
	v_sub_f32_e32 v187, v187, v82
	v_exp_f32_e32 v185, v185
	v_exp_f32_e32 v186, v186
	v_exp_f32_e32 v187, v187
	v_add_u32_e32 v196, 0xffffffeb, v112
	v_add_u32_e32 v197, 0xffffffea, v112
	v_add_u32_e32 v198, 0xffffffe9, v112
	v_cmp_gt_u32_e32 vcc, s91, v196
	v_cmp_gt_u32_e64 s[92:93], s91, v197
	v_cmp_gt_u32_e64 s[94:95], s91, v198
	v_cndmask_b32_e32 v185, 0, v185, vcc
	v_cndmask_b32_e64 v186, 0, v186, s[92:93]
	v_cndmask_b32_e64 v187, 0, v187, s[94:95]
	v_add_f32_e32 v103, v103, v185
	v_add_f32_e32 v103, v103, v186
	v_add_f32_e32 v103, v103, v187
	v_sub_f32_e32 v188, v188, v82
	v_sub_f32_e32 v189, v189, v82
	v_sub_f32_e32 v190, v190, v82
	v_exp_f32_e32 v188, v188
	v_exp_f32_e32 v189, v189
	v_exp_f32_e32 v190, v190
	v_add_u32_e32 v196, 0xffffffe8, v112
	v_add_u32_e32 v197, 0xffffffe7, v112
	v_add_u32_e32 v198, 0xffffffe6, v112
	v_cmp_gt_u32_e32 vcc, s91, v196
	v_cmp_gt_u32_e64 s[92:93], s91, v197
	v_cmp_gt_u32_e64 s[94:95], s91, v198
	v_cndmask_b32_e32 v188, 0, v188, vcc
	v_cndmask_b32_e64 v189, 0, v189, s[92:93]
	v_cndmask_b32_e64 v190, 0, v190, s[94:95]
	v_add_f32_e32 v103, v103, v188
	v_add_f32_e32 v103, v103, v189
	v_add_f32_e32 v103, v103, v190
	v_sub_f32_e32 v191, v191, v82
	v_sub_f32_e32 v192, v192, v82
	v_sub_f32_e32 v193, v193, v82
	v_exp_f32_e32 v191, v191
	v_exp_f32_e32 v192, v192
	v_exp_f32_e32 v193, v193
	v_add_u32_e32 v196, 0xffffffe5, v112
	v_add_u32_e32 v197, 0xffffffe4, v112
	v_add_u32_e32 v198, 0xffffffe3, v112
	v_cmp_gt_u32_e32 vcc, s91, v196
	v_cmp_gt_u32_e64 s[92:93], s91, v197
	v_cmp_gt_u32_e64 s[94:95], s91, v198
	v_cndmask_b32_e32 v191, 0, v191, vcc
	v_cndmask_b32_e64 v192, 0, v192, s[92:93]
	v_cndmask_b32_e64 v193, 0, v193, s[94:95]
	v_add_f32_e32 v103, v103, v191
	v_add_f32_e32 v103, v103, v192
	v_add_f32_e32 v103, v103, v193
	v_sub_f32_e32 v194, v194, v82
	v_sub_f32_e32 v195, v195, v82
	v_exp_f32_e32 v194, v194
	v_exp_f32_e32 v195, v195
	v_add_u32_e32 v196, 0xffffffe2, v112
	v_add_u32_e32 v197, 0xffffffe1, v112
	v_cmp_gt_u32_e32 vcc, s91, v196
	v_cmp_gt_u32_e64 s[92:93], s91, v197
	s_nop 0
	v_cndmask_b32_e32 v194, 0, v194, vcc
	v_cndmask_b32_e64 v195, 0, v195, s[92:93]
	v_add_f32_e32 v103, v103, v194
	v_add_f32_e32 v103, v103, v195
	v_cvt_pk_bf16_f32 v104, v164, v165
	v_cvt_pk_bf16_f32 v105, v166, v167
	v_cvt_pk_bf16_f32 v106, v168, v169
	v_cvt_pk_bf16_f32 v107, v170, v171
	ds_write_b128 v101, v[104:107]
	s_nop 0
	v_cvt_pk_bf16_f32 v104, v172, v173
	v_cvt_pk_bf16_f32 v105, v174, v175
	v_cvt_pk_bf16_f32 v106, v176, v177
	v_cvt_pk_bf16_f32 v107, v178, v179
	ds_write_b128 v101, v[104:107] offset:16
	s_nop 0
	v_cvt_pk_bf16_f32 v104, v180, v181
	v_cvt_pk_bf16_f32 v105, v182, v183
	v_cvt_pk_bf16_f32 v106, v184, v185
	v_cvt_pk_bf16_f32 v107, v186, v187
	ds_write_b128 v101, v[104:107] offset:32
	s_nop 0
	v_cvt_pk_bf16_f32 v104, v188, v189
	v_cvt_pk_bf16_f32 v105, v190, v191
	v_cvt_pk_bf16_f32 v106, v192, v193
	v_cvt_pk_bf16_f32 v107, v194, v195
	ds_write_b128 v101, v[104:107] offset:48
	s_branch .Lswa_pdone_3

; __device__ __forceinline__ unsigned pack2(float a, float b) { return (unsigned)f2bf(a) | ((unsigned)f2bf(b) << 16); }
; template <int DH, int MODE>
; __device__ void attn_item(const Params& p, int layer, int b, int blk, int head, char* smem) {
;     ...
;         float alpha = __builtin_amdgcn_exp2f(m_run - m_new);
;         float psum = 0.f;
; #pragma unroll 2
;         for (int s8 = 0; s8 < 4; ++s8) {
;           float4 va = s4[2 * s8], vb = s4[2 * s8 + 1];
;           float e[8] = {va.x, va.y, va.z, va.w, vb.x, vb.y, vb.z, vb.w};
;           float pv[8];
; #pragma unroll
;           for (int k = 0; k < 8; ++k) {
;             int kj = kjb + s8 * 8 + k;
;             bool valid = (kj > row) && (kj <= row + 128);
;             float pe = valid ? __builtin_amdgcn_exp2f(e[k] - m_new) : 0.f;
;             pv[k] = pe;
;             psum += pe;
;           }
;           uint4 ov;
;           ov.x = pack2(pv[0], pv[1]); ov.y = pack2(pv[2], pv[3]);
;           ov.z = pack2(pv[4], pv[5]); ov.w = pack2(pv[6], pv[7]);
;           *reinterpret_cast<uint4*>(prow + s8 * 16) = ov;
;         }
;         psum += __shfl_xor(psum, 1);
;         l_run = l_run * alpha + psum;
;         m_run = m_new;
;         if (half == 0) alpha_s[row] = alpha;
.Lswa_pdone_3:
	s_setprio 0
	v_sub_f32_e32 v101, v87, v82
	ds_bpermute_b32 v87, v83, v103
	v_exp_f32_e32 v83, v101
	s_and_saveexec_b64 s[6:7], s[4:5]
	ds_write_b32 v97, v83 offset:8192
	s_or_b64 exec, exec, s[6:7]
	s_waitcnt lgkmcnt(0)
	v_add_f32_e32 v101, v103, v87
	v_fmac_f32_e32 v101, v88, v83
	v_mov_b32_e32 v87, v82
	v_mov_b32_e32 v88, v101

; template <int DH, int MODE>
; __device__ void attn_item(const Params& p, int layer, int b, int blk, int head, char* smem) {
;     ...
;       if (MODE == 0) {
;         const int kjb = kj0 + half * 32;
;         float tmax = -1e30f;
; #pragma unroll
;         for (int c = 0; c < 8; ++c) {
;           float4 v = s4[c];
;           float e[4] = {v.x, v.y, v.z, v.w};
; #pragma unroll
;           for (int k = 0; k < 4; ++k) {
;             int kj = kjb + c * 4 + k;
;             bool valid = (kj > row) && (kj <= row + 128);
;             tmax = valid ? fmaxf(tmax, e[k]) : tmax;
;           }
;         }
;         tmax = fmaxf(tmax, __shfl_xor(tmax, 1));
.LBB0_487:
	s_or_b64 exec, exec, s[14:15]
	s_add_i32 s89, s89, 1
	s_min_i32 s14, s89, s87
	s_add_i32 s14, s14, s86
	s_lshl_b32 s14, s14, 6
	s_add_i32 s14, s14, s88
	s_ashr_i32 s15, s14, 31
	s_add_u32 s14, s14, s84
	s_addc_u32 s15, s15, 0
	s_waitcnt lgkmcnt(0)
	s_barrier
	ds_write_b16 v96, v48
	ds_write_b16_d16_hi v96, v48 offset:64
	ds_write_b16 v96, v49 offset:128
	ds_write_b16_d16_hi v96, v49 offset:192
	ds_write_b16 v96, v50 offset:256
	ds_write_b16_d16_hi v96, v50 offset:320
	ds_write_b16 v96, v51 offset:384
	ds_write_b16_d16_hi v96, v51 offset:448
	s_waitcnt vmcnt(0)
	ds_write_b16 v96, v52 offset:2048
	ds_write_b16_d16_hi v96, v52 offset:2112
	ds_write_b16 v96, v53 offset:2176
	ds_write_b16_d16_hi v96, v53 offset:2240
	ds_write_b16 v96, v54 offset:2304
	ds_write_b16_d16_hi v96, v54 offset:2368
	ds_write_b16 v96, v55 offset:2432
	ds_write_b16_d16_hi v96, v55 offset:2496
	v_lshl_add_u64 v[48:49], s[14:15], 0, v[66:67]
	v_mad_u64_u32 v[52:53], s[20:21], v48, s63, v[76:77]
	v_or_b32_e32 v48, s14, v72
	v_mad_i32_i24 v53, v49, s63, v53
	v_mad_u64_u32 v[54:55], s[20:21], v48, s63, v[78:79]
	v_add_co_u32_e32 v48, vcc, 0x4c000, v52
	v_mad_i32_i24 v55, s15, v160, v55
	s_nop 0
	v_addc_co_u32_e32 v49, vcc, 0, v53, vcc
	global_load_dwordx4 v[60:63], v[48:49], off
	s_nop 0
	global_load_dwordx4 v[48:51], v[54:55], off
	global_load_dwordx4 v[56:59], v[52:53], off
	s_nop 0
	global_load_dwordx4 v[52:55], v[54:55], off offset:64
	s_and_saveexec_b64 s[54:55], s[52:53]
	s_cbranch_execz .LBB0_509
	v_or_b32_e32 v101, s16, v89
	s_setprio 1
	s_movk_i32 s91, 0x80
	ds_read_b128 v[164:167], v90 offset:16384
	ds_read_b128 v[168:171], v90 offset:16400
	ds_read_b128 v[172:175], v90 offset:16416
	ds_read_b128 v[176:179], v90 offset:16432
	ds_read_b128 v[180:183], v90 offset:16448
	ds_read_b128 v[184:187], v90 offset:16464
	ds_read_b128 v[188:191], v90 offset:16480
	ds_read_b128 v[192:195], v90 offset:16496
	v_sub_u32_e32 v102, v80, v101
	v_mov_b32_e32 v83, 0xf149f2ca
	v_add_u32_e32 v103, -31, v102
	v_cmp_gt_u32_e32 vcc, 0x61, v103
	s_cmp_eq_u64 vcc, exec
	s_cbranch_scc1 .Lswa_tfast_2
	v_mov_b32_e32 v161, v102
	v_add_u32_e32 v162, -1, v102
	v_add_u32_e32 v163, -2, v102
	v_cmp_gt_u32_e32 vcc, s91, v161
	v_cmp_gt_u32_e64 s[92:93], s91, v162
	v_cmp_gt_u32_e64 s[94:95], s91, v163
	s_waitcnt lgkmcnt(7)
	v_cndmask_b32_e32 v200, v83, v164, vcc
	v_cndmask_b32_e64 v201, v83, v165, s[92:93]
	v_cndmask_b32_e64 v202, v83, v166, s[94:95]
	v_add_u32_e32 v161, -3, v102
	v_add_u32_e32 v162, -4, v102
	v_add_u32_e32 v163, -5, v102
	v_cmp_gt_u32_e32 vcc, s91, v161
	v_cmp_gt_u32_e64 s[92:93], s91, v162
	v_cmp_gt_u32_e64 s[94:95], s91, v163
	s_waitcnt lgkmcnt(6)
	v_cndmask_b32_e32 v203, v83, v167, vcc
	v_cndmask_b32_e64 v204, v83, v168, s[92:93]
	v_cndmask_b32_e64 v205, v83, v169, s[94:95]
	v_add_u32_e32 v161, -6, v102
	v_add_u32_e32 v162, -7, v102
	v_add_u32_e32 v163, -8, v102
	v_cmp_gt_u32_e32 vcc, s91, v161
	v_cmp_gt_u32_e64 s[92:93], s91, v162
	v_cmp_gt_u32_e64 s[94:95], s91, v163
	s_waitcnt lgkmcnt(5)
	v_cndmask_b32_e32 v206, v83, v170, vcc
	v_cndmask_b32_e64 v207, v83, v171, s[92:93]
	v_cndmask_b32_e64 v208, v83, v172, s[94:95]
	v_add_u32_e32 v161, -9, v102
	v_add_u32_e32 v162, -10, v102
	v_add_u32_e32 v163, -11, v102
	v_cmp_gt_u32_e32 vcc, s91, v161
	v_cmp_gt_u32_e64 s[92:93], s91, v162
	v_cmp_gt_u32_e64 s[94:95], s91, v163
	v_cndmask_b32_e32 v209, v83, v173, vcc
	v_cndmask_b32_e64 v210, v83, v174, s[92:93]
	v_cndmask_b32_e64 v211, v83, v175, s[94:95]
	v_add_u32_e32 v161, -12, v102
	v_add_u32_e32 v162, -13, v102
	v_add_u32_e32 v163, -14, v102
	v_cmp_gt_u32_e32 vcc, s91, v161
	v_cmp_gt_u32_e64 s[92:93], s91, v162
	v_cmp_gt_u32_e64 s[94:95], s91, v163
	s_waitcnt lgkmcnt(4)
	v_cndmask_b32_e32 v212, v83, v176, vcc
	v_cndmask_b32_e64 v213, v83, v177, s[92:93]
	v_cndmask_b32_e64 v214, v83, v178, s[94:95]
	v_add_u32_e32 v161, -15, v102
	v_add_u32_e32 v162, -16, v102
	v_add_u32_e32 v163, 0xffffffef, v102
	v_cmp_gt_u32_e32 vcc, s91, v161
	v_cmp_gt_u32_e64 s[92:93], s91, v162
	v_cmp_gt_u32_e64 s[94:95], s91, v163
	s_waitcnt lgkmcnt(3)
	v_cndmask_b32_e32 v215, v83, v179, vcc
	v_cndmask_b32_e64 v216, v83, v180, s[92:93]
	v_cndmask_b32_e64 v217, v83, v181, s[94:95]
	v_add_u32_e32 v161, 0xffffffee, v102
	v_add_u32_e32 v162, 0xffffffed, v102
	v_add_u32_e32 v163, 0xffffffec, v102
	v_cmp_gt_u32_e32 vcc, s91, v161
	v_cmp_gt_u32_e64 s[92:93], s91, v162
	v_cmp_gt_u32_e64 s[94:95], s91, v163
	s_waitcnt lgkmcnt(2)
	v_cndmask_b32_e32 v218, v83, v182, vcc
	v_cndmask_b32_e64 v219, v83, v183, s[92:93]
	v_cndmask_b32_e64 v220, v83, v184, s[94:95]
	v_add_u32_e32 v161, 0xffffffeb, v102
	v_add_u32_e32 v162, 0xffffffea, v102
	v_add_u32_e32 v163, 0xffffffe9, v102
	v_cmp_gt_u32_e32 vcc, s91, v161
	v_cmp_gt_u32_e64 s[92:93], s91, v162
	v_cmp_gt_u32_e64 s[94:95], s91, v163
	v_cndmask_b32_e32 v221, v83, v185, vcc
	v_cndmask_b32_e64 v222, v83, v186, s[92:93]
	v_cndmask_b32_e64 v223, v83, v187, s[94:95]
	v_add_u32_e32 v161, 0xffffffe8, v102
	v_add_u32_e32 v162, 0xffffffe7, v102
	v_add_u32_e32 v163, 0xffffffe6, v102
	v_cmp_gt_u32_e32 vcc, s91, v161
	v_cmp_gt_u32_e64 s[92:93], s91, v162
	v_cmp_gt_u32_e64 s[94:95], s91, v163
	s_waitcnt lgkmcnt(1)
	v_cndmask_b32_e32 v224, v83, v188, vcc
	v_cndmask_b32_e64 v225, v83, v189, s[92:93]
	v_cndmask_b32_e64 v226, v83, v190, s[94:95]
	v_add_u32_e32 v161, 0xffffffe5, v102
	v_add_u32_e32 v162, 0xffffffe4, v102
	v_add_u32_e32 v163, 0xffffffe3, v102
	v_cmp_gt_u32_e32 vcc, s91, v161
	v_cmp_gt_u32_e64 s[92:93], s91, v162
	v_cmp_gt_u32_e64 s[94:95], s91, v163
	s_waitcnt lgkmcnt(0)
	v_cndmask_b32_e32 v227, v83, v191, vcc
	v_cndmask_b32_e64 v228, v83, v192, s[92:93]
	v_cndmask_b32_e64 v229, v83, v193, s[94:95]
	v_add_u32_e32 v161, 0xffffffe2, v102
	v_add_u32_e32 v162, 0xffffffe1, v102
	v_cmp_gt_u32_e32 vcc, s91, v161
	v_cmp_gt_u32_e64 s[92:93], s91, v162
	s_nop 0
	v_cndmask_b32_e32 v230, v83, v194, vcc
	v_cndmask_b32_e64 v231, v83, v195, s[92:93]
	v_max3_f32 v200, v200, v201, v202
	v_max3_f32 v203, v203, v204, v205
	v_max3_f32 v206, v206, v207, v208
	v_max3_f32 v209, v209, v210, v211
	v_max3_f32 v212, v212, v213, v214
	v_max3_f32 v215, v215, v216, v217
	v_max3_f32 v218, v218, v219, v220
	v_max3_f32 v221, v221, v222, v223
	v_max3_f32 v224, v224, v225, v226
	v_max3_f32 v227, v227, v228, v229
	v_max_f32_e32 v230, v230, v231
	v_max3_f32 v200, v200, v203, v206
	v_max3_f32 v209, v209, v212, v215
	v_max3_f32 v218, v218, v221, v224
	v_max_f32_e32 v227, v227, v230
	v_max3_f32 v200, v200, v209, v218
	v_max_f32_e32 v200, v200, v227
	v_mov_b32_e32 v82, v200
	s_branch .Lswa_tdone_2

; template <int DH, int MODE>
; __device__ void attn_item(const Params& p, int layer, int b, int blk, int head, char* smem) {
;     ...
;         tmax = fmaxf(tmax, __shfl_xor(tmax, 1));
;         float m_new = fmaxf(m_run, tmax);
;         float alpha = __builtin_amdgcn_exp2f(m_run - m_new);
;         float psum = 0.f;
; #pragma unroll 2
;         for (int s8 = 0; s8 < 4; ++s8) {
;           float4 va = s4[2 * s8], vb = s4[2 * s8 + 1];
;           float e[8] = {va.x, va.y, va.z, va.w, vb.x, vb.y, vb.z, vb.w};
;           float pv[8];
; #pragma unroll
;           for (int k = 0; k < 8; ++k) {
;             int kj = kjb + s8 * 8 + k;
;             bool valid = (kj > row) && (kj <= row + 128);
;             float pe = valid ? __builtin_amdgcn_exp2f(e[k] - m_new) : 0.f;
;             pv[k] = pe;
;             psum += pe;
.Lswa_tdone_2:
	v_cmp_lt_i32_e32 vcc, v157, v158
	s_mov_b32 s90, 0
	v_mov_b32_e32 v103, 0
	v_cndmask_b32_e32 v83, v156, v157, vcc
	v_lshlrev_b32_e32 v83, 2, v83
	ds_bpermute_b32 v101, v83, v82
	v_mov_b32_e32 v102, v91
	s_waitcnt lgkmcnt(0)
	v_max3_f32 v82, v87, v82, v101
	v_mov_b32_e32 v101, v93
	s_setprio 1
	s_movk_i32 s91, 0x80
	v_sub_u32_e32 v112, v80, v92
	v_add_u32_e32 v113, -31, v112
	v_cmp_gt_u32_e32 vcc, 0x61, v113
	s_cmp_eq_u64 vcc, exec
	s_cbranch_scc1 .Lswa_pfast_2
	v_sub_f32_e32 v164, v164, v82
	v_sub_f32_e32 v165, v165, v82
	v_sub_f32_e32 v166, v166, v82
	v_exp_f32_e32 v164, v164
	v_exp_f32_e32 v165, v165
	v_exp_f32_e32 v166, v166
	v_mov_b32_e32 v196, v112
	v_add_u32_e32 v197, -1, v112
	v_add_u32_e32 v198, -2, v112
	v_cmp_gt_u32_e32 vcc, s91, v196
	v_cmp_gt_u32_e64 s[92:93], s91, v197
	v_cmp_gt_u32_e64 s[94:95], s91, v198
	v_cndmask_b32_e32 v164, 0, v164, vcc
	v_cndmask_b32_e64 v165, 0, v165, s[92:93]
	v_cndmask_b32_e64 v166, 0, v166, s[94:95]
	v_add_f32_e32 v103, v103, v164
	v_add_f32_e32 v103, v103, v165
	v_add_f32_e32 v103, v103, v166
	v_sub_f32_e32 v167, v167, v82
	v_sub_f32_e32 v168, v168, v82
	v_sub_f32_e32 v169, v169, v82
	v_exp_f32_e32 v167, v167
	v_exp_f32_e32 v168, v168
	v_exp_f32_e32 v169, v169
	v_add_u32_e32 v196, -3, v112
	v_add_u32_e32 v197, -4, v112
	v_add_u32_e32 v198, -5, v112
	v_cmp_gt_u32_e32 vcc, s91, v196
	v_cmp_gt_u32_e64 s[92:93], s91, v197
	v_cmp_gt_u32_e64 s[94:95], s91, v198
	v_cndmask_b32_e32 v167, 0, v167, vcc
	v_cndmask_b32_e64 v168, 0, v168, s[92:93]
	v_cndmask_b32_e64 v169, 0, v169, s[94:95]
	v_add_f32_e32 v103, v103, v167
	v_add_f32_e32 v103, v103, v168
	v_add_f32_e32 v103, v103, v169
	v_sub_f32_e32 v170, v170, v82
	v_sub_f32_e32 v171, v171, v82
	v_sub_f32_e32 v172, v172, v82
	v_exp_f32_e32 v170, v170
	v_exp_f32_e32 v171, v171
	v_exp_f32_e32 v172, v172
	v_add_u32_e32 v196, -6, v112
	v_add_u32_e32 v197, -7, v112
	v_add_u32_e32 v198, -8, v112
	v_cmp_gt_u32_e32 vcc, s91, v196
	v_cmp_gt_u32_e64 s[92:93], s91, v197
	v_cmp_gt_u32_e64 s[94:95], s91, v198
	v_cndmask_b32_e32 v170, 0, v170, vcc
	v_cndmask_b32_e64 v171, 0, v171, s[92:93]
	v_cndmask_b32_e64 v172, 0, v172, s[94:95]
	v_add_f32_e32 v103, v103, v170
	v_add_f32_e32 v103, v103, v171
	v_add_f32_e32 v103, v103, v172
	v_sub_f32_e32 v173, v173, v82
	v_sub_f32_e32 v174, v174, v82
	v_sub_f32_e32 v175, v175, v82
	v_exp_f32_e32 v173, v173
	v_exp_f32_e32 v174, v174
	v_exp_f32_e32 v175, v175
	v_add_u32_e32 v196, -9, v112
	v_add_u32_e32 v197, -10, v112
	v_add_u32_e32 v198, -11, v112
	v_cmp_gt_u32_e32 vcc, s91, v196
	v_cmp_gt_u32_e64 s[92:93], s91, v197
	v_cmp_gt_u32_e64 s[94:95], s91, v198
	v_cndmask_b32_e32 v173, 0, v173, vcc
	v_cndmask_b32_e64 v174, 0, v174, s[92:93]
	v_cndmask_b32_e64 v175, 0, v175, s[94:95]
	v_add_f32_e32 v103, v103, v173
	v_add_f32_e32 v103, v103, v174
	v_add_f32_e32 v103, v103, v175
	v_sub_f32_e32 v176, v176, v82
	v_sub_f32_e32 v177, v177, v82
	v_sub_f32_e32 v178, v178, v82
	v_exp_f32_e32 v176, v176
	v_exp_f32_e32 v177, v177
	v_exp_f32_e32 v178, v178
	v_add_u32_e32 v196, -12, v112
	v_add_u32_e32 v197, -13, v112
	v_add_u32_e32 v198, -14, v112
	v_cmp_gt_u32_e32 vcc, s91, v196
	v_cmp_gt_u32_e64 s[92:93], s91, v197
	v_cmp_gt_u32_e64 s[94:95], s91, v198
	v_cndmask_b32_e32 v176, 0, v176, vcc
	v_cndmask_b32_e64 v177, 0, v177, s[92:93]
	v_cndmask_b32_e64 v178, 0, v178, s[94:95]
	v_add_f32_e32 v103, v103, v176
	v_add_f32_e32 v103, v103, v177
	v_add_f32_e32 v103, v103, v178
	v_sub_f32_e32 v179, v179, v82
	v_sub_f32_e32 v180, v180, v82
	v_sub_f32_e32 v181, v181, v82
	v_exp_f32_e32 v179, v179
	v_exp_f32_e32 v180, v180
	v_exp_f32_e32 v181, v181
	v_add_u32_e32 v196, -15, v112
	v_add_u32_e32 v197, -16, v112
	v_add_u32_e32 v198, 0xffffffef, v112
	v_cmp_gt_u32_e32 vcc, s91, v196
	v_cmp_gt_u32_e64 s[92:93], s91, v197
	v_cmp_gt_u32_e64 s[94:95], s91, v198
	v_cndmask_b32_e32 v179, 0, v179, vcc
; __device__ __forceinline__ unsigned pack2(float a, float b) { return (unsigned)f2bf(a) | ((unsigned)f2bf(b) << 16); }
; template <int DH, int MODE>
; __device__ void attn_item(const Params& p, int layer, int b, int blk, int head, char* smem) {
;     ...
; #pragma unroll 2
;         for (int s8 = 0; s8 < 4; ++s8) {
;           float4 va = s4[2 * s8], vb = s4[2 * s8 + 1];
;           float e[8] = {va.x, va.y, va.z, va.w, vb.x, vb.y, vb.z, vb.w};
;           float pv[8];
; #pragma unroll
;           for (int k = 0; k < 8; ++k) {
;             int kj = kjb + s8 * 8 + k;
;             bool valid = (kj > row) && (kj <= row + 128);
;             float pe = valid ? __builtin_amdgcn_exp2f(e[k] - m_new) : 0.f;
;             pv[k] = pe;
;             psum += pe;
;           }
;           uint4 ov;
;           ov.x = pack2(pv[0], pv[1]); ov.y = pack2(pv[2], pv[3]);
;           ov.z = pack2(pv[4], pv[5]); ov.w = pack2(pv[6], pv[7]);
;           *reinterpret_cast<uint4*>(prow + s8 * 16) = ov;
;         }
	v_cndmask_b32_e64 v180, 0, v180, s[92:93]
	v_cndmask_b32_e64 v181, 0, v181, s[94:95]
	v_add_f32_e32 v103, v103, v179
	v_add_f32_e32 v103, v103, v180
	v_add_f32_e32 v103, v103, v181
	v_sub_f32_e32 v182, v182, v82
	v_sub_f32_e32 v183, v183, v82
	v_sub_f32_e32 v184, v184, v82
	v_exp_f32_e32 v182, v182
	v_exp_f32_e32 v183, v183
	v_exp_f32_e32 v184, v184
	v_add_u32_e32 v196, 0xffffffee, v112
	v_add_u32_e32 v197, 0xffffffed, v112
	v_add_u32_e32 v198, 0xffffffec, v112
	v_cmp_gt_u32_e32 vcc, s91, v196
	v_cmp_gt_u32_e64 s[92:93], s91, v197
	v_cmp_gt_u32_e64 s[94:95], s91, v198
	v_cndmask_b32_e32 v182, 0, v182, vcc
	v_cndmask_b32_e64 v183, 0, v183, s[92:93]
	v_cndmask_b32_e64 v184, 0, v184, s[94:95]
	v_add_f32_e32 v103, v103, v182
	v_add_f32_e32 v103, v103, v183
	v_add_f32_e32 v103, v103, v184
	v_sub_f32_e32 v185, v185, v82
	v_sub_f32_e32 v186, v186, v82
	v_sub_f32_e32 v187, v187, v82
	v_exp_f32_e32 v185, v185
	v_exp_f32_e32 v186, v186
	v_exp_f32_e32 v187, v187
	v_add_u32_e32 v196, 0xffffffeb, v112
	v_add_u32_e32 v197, 0xffffffea, v112
	v_add_u32_e32 v198, 0xffffffe9, v112
	v_cmp_gt_u32_e32 vcc, s91, v196
	v_cmp_gt_u32_e64 s[92:93], s91, v197
	v_cmp_gt_u32_e64 s[94:95], s91, v198
	v_cndmask_b32_e32 v185, 0, v185, vcc
	v_cndmask_b32_e64 v186, 0, v186, s[92:93]
	v_cndmask_b32_e64 v187, 0, v187, s[94:95]
	v_add_f32_e32 v103, v103, v185
	v_add_f32_e32 v103, v103, v186
	v_add_f32_e32 v103, v103, v187
	v_sub_f32_e32 v188, v188, v82
	v_sub_f32_e32 v189, v189, v82
	v_sub_f32_e32 v190, v190, v82
	v_exp_f32_e32 v188, v188
	v_exp_f32_e32 v189, v189
	v_exp_f32_e32 v190, v190
	v_add_u32_e32 v196, 0xffffffe8, v112
	v_add_u32_e32 v197, 0xffffffe7, v112
	v_add_u32_e32 v198, 0xffffffe6, v112
	v_cmp_gt_u32_e32 vcc, s91, v196
	v_cmp_gt_u32_e64 s[92:93], s91, v197
	v_cmp_gt_u32_e64 s[94:95], s91, v198
	v_cndmask_b32_e32 v188, 0, v188, vcc
	v_cndmask_b32_e64 v189, 0, v189, s[92:93]
	v_cndmask_b32_e64 v190, 0, v190, s[94:95]
	v_add_f32_e32 v103, v103, v188
	v_add_f32_e32 v103, v103, v189
	v_add_f32_e32 v103, v103, v190
	v_sub_f32_e32 v191, v191, v82
	v_sub_f32_e32 v192, v192, v82
	v_sub_f32_e32 v193, v193, v82
	v_exp_f32_e32 v191, v191
	v_exp_f32_e32 v192, v192
	v_exp_f32_e32 v193, v193
	v_add_u32_e32 v196, 0xffffffe5, v112
	v_add_u32_e32 v197, 0xffffffe4, v112
	v_add_u32_e32 v198, 0xffffffe3, v112
	v_cmp_gt_u32_e32 vcc, s91, v196
	v_cmp_gt_u32_e64 s[92:93], s91, v197
	v_cmp_gt_u32_e64 s[94:95], s91, v198
	v_cndmask_b32_e32 v191, 0, v191, vcc
	v_cndmask_b32_e64 v192, 0, v192, s[92:93]
	v_cndmask_b32_e64 v193, 0, v193, s[94:95]
	v_add_f32_e32 v103, v103, v191
	v_add_f32_e32 v103, v103, v192
	v_add_f32_e32 v103, v103, v193
	v_sub_f32_e32 v194, v194, v82
	v_sub_f32_e32 v195, v195, v82
	v_exp_f32_e32 v194, v194
	v_exp_f32_e32 v195, v195
	v_add_u32_e32 v196, 0xffffffe2, v112
	v_add_u32_e32 v197, 0xffffffe1, v112
	v_cmp_gt_u32_e32 vcc, s91, v196
	v_cmp_gt_u32_e64 s[92:93], s91, v197
	s_nop 0
	v_cndmask_b32_e32 v194, 0, v194, vcc
	v_cndmask_b32_e64 v195, 0, v195, s[92:93]
	v_add_f32_e32 v103, v103, v194
	v_add_f32_e32 v103, v103, v195
	v_cvt_pk_bf16_f32 v104, v164, v165
	v_cvt_pk_bf16_f32 v105, v166, v167
	v_cvt_pk_bf16_f32 v106, v168, v169
	v_cvt_pk_bf16_f32 v107, v170, v171
	ds_write_b128 v101, v[104:107]
	s_nop 0
	v_cvt_pk_bf16_f32 v104, v172, v173
	v_cvt_pk_bf16_f32 v105, v174, v175
	v_cvt_pk_bf16_f32 v106, v176, v177
	v_cvt_pk_bf16_f32 v107, v178, v179
	ds_write_b128 v101, v[104:107] offset:16
	s_nop 0
	v_cvt_pk_bf16_f32 v104, v180, v181
	v_cvt_pk_bf16_f32 v105, v182, v183
	v_cvt_pk_bf16_f32 v106, v184, v185
	v_cvt_pk_bf16_f32 v107, v186, v187
	ds_write_b128 v101, v[104:107] offset:32
	s_nop 0
	v_cvt_pk_bf16_f32 v104, v188, v189
	v_cvt_pk_bf16_f32 v105, v190, v191
	v_cvt_pk_bf16_f32 v106, v192, v193
	v_cvt_pk_bf16_f32 v107, v194, v195
	ds_write_b128 v101, v[104:107] offset:48
	s_branch .Lswa_pdone_2

; __device__ __forceinline__ unsigned pack2(float a, float b) { return (unsigned)f2bf(a) | ((unsigned)f2bf(b) << 16); }
; template <int DH, int MODE>
; __device__ void attn_item(const Params& p, int layer, int b, int blk, int head, char* smem) {
;     ...
;         float alpha = __builtin_amdgcn_exp2f(m_run - m_new);
;         float psum = 0.f;
; #pragma unroll 2
;         for (int s8 = 0; s8 < 4; ++s8) {
;           float4 va = s4[2 * s8], vb = s4[2 * s8 + 1];
;           float e[8] = {va.x, va.y, va.z, va.w, vb.x, vb.y, vb.z, vb.w};
;           float pv[8];
; #pragma unroll
;           for (int k = 0; k < 8; ++k) {
;             int kj = kjb + s8 * 8 + k;
;             bool valid = (kj > row) && (kj <= row + 128);
;             float pe = valid ? __builtin_amdgcn_exp2f(e[k] - m_new) : 0.f;
;             pv[k] = pe;
;             psum += pe;
;           }
;           uint4 ov;
;           ov.x = pack2(pv[0], pv[1]); ov.y = pack2(pv[2], pv[3]);
;           ov.z = pack2(pv[4], pv[5]); ov.w = pack2(pv[6], pv[7]);
;           *reinterpret_cast<uint4*>(prow + s8 * 16) = ov;
;         }
;         psum += __shfl_xor(psum, 1);
;         l_run = l_run * alpha + psum;
;         m_run = m_new;
;         if (half == 0) alpha_s[row] = alpha;
.Lswa_pdone_2:
	s_setprio 0
	v_sub_f32_e32 v101, v87, v82
	ds_bpermute_b32 v87, v83, v103
	v_exp_f32_e32 v83, v101
	s_and_saveexec_b64 s[14:15], s[12:13]
	ds_write_b32 v97, v83 offset:8192
	s_or_b64 exec, exec, s[14:15]
	s_waitcnt lgkmcnt(0)
	v_add_f32_e32 v101, v103, v87
	v_fmac_f32_e32 v101, v88, v83
	v_mov_b32_e32 v87, v82
	v_mov_b32_e32 v88, v101

; template <int DH, int MODE>
; __device__ void attn_item(const Params& p, int layer, int b, int blk, int head, char* smem) {
;     ...
;       if (MODE == 0) {
;         const int kjb = kj0 + half * 32;
;         float tmax = -1e30f;
; #pragma unroll
;         for (int c = 0; c < 8; ++c) {
;           float4 v = s4[c];
;           float e[4] = {v.x, v.y, v.z, v.w};
; #pragma unroll
;           for (int k = 0; k < 4; ++k) {
;             int kj = kjb + c * 4 + k;
;             bool valid = (kj > row) && (kj <= row + 128);
;             tmax = valid ? fmaxf(tmax, e[k]) : tmax;
;           }
;         }
;         tmax = fmaxf(tmax, __shfl_xor(tmax, 1));
.LBB0_808:
	s_or_b64 exec, exec, s[14:15]
	s_add_i32 s89, s89, 1
	s_min_i32 s14, s89, s87
	s_add_i32 s14, s14, s86
	s_lshl_b32 s14, s14, 6
	s_add_i32 s14, s14, s88
	s_ashr_i32 s15, s14, 31
	s_add_u32 s14, s14, s84
	s_addc_u32 s15, s15, 0
	s_waitcnt lgkmcnt(0)
	s_barrier
	ds_write_b16 v96, v48
	ds_write_b16_d16_hi v96, v48 offset:64
	ds_write_b16 v96, v49 offset:128
	ds_write_b16_d16_hi v96, v49 offset:192
	ds_write_b16 v96, v50 offset:256
	ds_write_b16_d16_hi v96, v50 offset:320
	ds_write_b16 v96, v51 offset:384
	ds_write_b16_d16_hi v96, v51 offset:448
	s_waitcnt vmcnt(0)
	ds_write_b16 v96, v52 offset:2048
	ds_write_b16_d16_hi v96, v52 offset:2112
	ds_write_b16 v96, v53 offset:2176
	ds_write_b16_d16_hi v96, v53 offset:2240
	ds_write_b16 v96, v54 offset:2304
	ds_write_b16_d16_hi v96, v54 offset:2368
	ds_write_b16 v96, v55 offset:2432
	ds_write_b16_d16_hi v96, v55 offset:2496
	v_lshl_add_u64 v[48:49], s[14:15], 0, v[66:67]
	v_mad_u64_u32 v[52:53], s[20:21], v48, s45, v[76:77]
	v_or_b32_e32 v48, s14, v72
	v_mad_i32_i24 v53, v49, s45, v53
	v_mad_u64_u32 v[54:55], s[20:21], v48, s45, v[78:79]
	v_add_co_u32_e32 v48, vcc, 0x4c000, v52
	v_mad_i32_i24 v55, s15, v160, v55
	s_nop 0
	v_addc_co_u32_e32 v49, vcc, 0, v53, vcc
	global_load_dwordx4 v[60:63], v[48:49], off
	s_nop 0
	global_load_dwordx4 v[48:51], v[54:55], off
	global_load_dwordx4 v[56:59], v[52:53], off
	s_nop 0
	global_load_dwordx4 v[52:55], v[54:55], off offset:64
	s_and_saveexec_b64 s[52:53], s[50:51]
	s_cbranch_execz .LBB0_830
	v_or_b32_e32 v101, s16, v89
	s_setprio 1
	s_movk_i32 s91, 0x80
	ds_read_b128 v[164:167], v90 offset:16384
	ds_read_b128 v[168:171], v90 offset:16400
	ds_read_b128 v[172:175], v90 offset:16416
	ds_read_b128 v[176:179], v90 offset:16432
	ds_read_b128 v[180:183], v90 offset:16448
	ds_read_b128 v[184:187], v90 offset:16464
	ds_read_b128 v[188:191], v90 offset:16480
	ds_read_b128 v[192:195], v90 offset:16496
	v_sub_u32_e32 v102, v80, v101
	v_mov_b32_e32 v83, 0xf149f2ca
	v_add_u32_e32 v103, -31, v102
	v_cmp_gt_u32_e32 vcc, 0x61, v103
	s_cmp_eq_u64 vcc, exec
	s_cbranch_scc1 .Lswa_tfast_1
	v_mov_b32_e32 v161, v102
	v_add_u32_e32 v162, -1, v102
	v_add_u32_e32 v163, -2, v102
	v_cmp_gt_u32_e32 vcc, s91, v161
	v_cmp_gt_u32_e64 s[92:93], s91, v162
	v_cmp_gt_u32_e64 s[94:95], s91, v163
	s_waitcnt lgkmcnt(7)
	v_cndmask_b32_e32 v200, v83, v164, vcc
	v_cndmask_b32_e64 v201, v83, v165, s[92:93]
	v_cndmask_b32_e64 v202, v83, v166, s[94:95]
	v_add_u32_e32 v161, -3, v102
	v_add_u32_e32 v162, -4, v102
	v_add_u32_e32 v163, -5, v102
	v_cmp_gt_u32_e32 vcc, s91, v161
	v_cmp_gt_u32_e64 s[92:93], s91, v162
	v_cmp_gt_u32_e64 s[94:95], s91, v163
	s_waitcnt lgkmcnt(6)
	v_cndmask_b32_e32 v203, v83, v167, vcc
	v_cndmask_b32_e64 v204, v83, v168, s[92:93]
	v_cndmask_b32_e64 v205, v83, v169, s[94:95]
	v_add_u32_e32 v161, -6, v102
	v_add_u32_e32 v162, -7, v102
	v_add_u32_e32 v163, -8, v102
	v_cmp_gt_u32_e32 vcc, s91, v161
	v_cmp_gt_u32_e64 s[92:93], s91, v162
	v_cmp_gt_u32_e64 s[94:95], s91, v163
	s_waitcnt lgkmcnt(5)
	v_cndmask_b32_e32 v206, v83, v170, vcc
	v_cndmask_b32_e64 v207, v83, v171, s[92:93]
	v_cndmask_b32_e64 v208, v83, v172, s[94:95]
	v_add_u32_e32 v161, -9, v102
	v_add_u32_e32 v162, -10, v102
	v_add_u32_e32 v163, -11, v102
	v_cmp_gt_u32_e32 vcc, s91, v161
	v_cmp_gt_u32_e64 s[92:93], s91, v162
	v_cmp_gt_u32_e64 s[94:95], s91, v163
	v_cndmask_b32_e32 v209, v83, v173, vcc
	v_cndmask_b32_e64 v210, v83, v174, s[92:93]
	v_cndmask_b32_e64 v211, v83, v175, s[94:95]
	v_add_u32_e32 v161, -12, v102
	v_add_u32_e32 v162, -13, v102
	v_add_u32_e32 v163, -14, v102
	v_cmp_gt_u32_e32 vcc, s91, v161
	v_cmp_gt_u32_e64 s[92:93], s91, v162
	v_cmp_gt_u32_e64 s[94:95], s91, v163
	s_waitcnt lgkmcnt(4)
	v_cndmask_b32_e32 v212, v83, v176, vcc
	v_cndmask_b32_e64 v213, v83, v177, s[92:93]
	v_cndmask_b32_e64 v214, v83, v178, s[94:95]
	v_add_u32_e32 v161, -15, v102
	v_add_u32_e32 v162, -16, v102
	v_add_u32_e32 v163, 0xffffffef, v102
	v_cmp_gt_u32_e32 vcc, s91, v161
	v_cmp_gt_u32_e64 s[92:93], s91, v162
	v_cmp_gt_u32_e64 s[94:95], s91, v163
	s_waitcnt lgkmcnt(3)
	v_cndmask_b32_e32 v215, v83, v179, vcc
	v_cndmask_b32_e64 v216, v83, v180, s[92:93]
	v_cndmask_b32_e64 v217, v83, v181, s[94:95]
	v_add_u32_e32 v161, 0xffffffee, v102
	v_add_u32_e32 v162, 0xffffffed, v102
	v_add_u32_e32 v163, 0xffffffec, v102
	v_cmp_gt_u32_e32 vcc, s91, v161
	v_cmp_gt_u32_e64 s[92:93], s91, v162
	v_cmp_gt_u32_e64 s[94:95], s91, v163
	s_waitcnt lgkmcnt(2)
	v_cndmask_b32_e32 v218, v83, v182, vcc
	v_cndmask_b32_e64 v219, v83, v183, s[92:93]
	v_cndmask_b32_e64 v220, v83, v184, s[94:95]
	v_add_u32_e32 v161, 0xffffffeb, v102
	v_add_u32_e32 v162, 0xffffffea, v102
	v_add_u32_e32 v163, 0xffffffe9, v102
	v_cmp_gt_u32_e32 vcc, s91, v161
	v_cmp_gt_u32_e64 s[92:93], s91, v162
	v_cmp_gt_u32_e64 s[94:95], s91, v163
	v_cndmask_b32_e32 v221, v83, v185, vcc
	v_cndmask_b32_e64 v222, v83, v186, s[92:93]
	v_cndmask_b32_e64 v223, v83, v187, s[94:95]
	v_add_u32_e32 v161, 0xffffffe8, v102
	v_add_u32_e32 v162, 0xffffffe7, v102
	v_add_u32_e32 v163, 0xffffffe6, v102
	v_cmp_gt_u32_e32 vcc, s91, v161
	v_cmp_gt_u32_e64 s[92:93], s91, v162
	v_cmp_gt_u32_e64 s[94:95], s91, v163
	s_waitcnt lgkmcnt(1)
	v_cndmask_b32_e32 v224, v83, v188, vcc
	v_cndmask_b32_e64 v225, v83, v189, s[92:93]
	v_cndmask_b32_e64 v226, v83, v190, s[94:95]
	v_add_u32_e32 v161, 0xffffffe5, v102
	v_add_u32_e32 v162, 0xffffffe4, v102
	v_add_u32_e32 v163, 0xffffffe3, v102
	v_cmp_gt_u32_e32 vcc, s91, v161
	v_cmp_gt_u32_e64 s[92:93], s91, v162
	v_cmp_gt_u32_e64 s[94:95], s91, v163
	s_waitcnt lgkmcnt(0)
	v_cndmask_b32_e32 v227, v83, v191, vcc
	v_cndmask_b32_e64 v228, v83, v192, s[92:93]
	v_cndmask_b32_e64 v229, v83, v193, s[94:95]
	v_add_u32_e32 v161, 0xffffffe2, v102
	v_add_u32_e32 v162, 0xffffffe1, v102
	v_cmp_gt_u32_e32 vcc, s91, v161
	v_cmp_gt_u32_e64 s[92:93], s91, v162
	s_nop 0
	v_cndmask_b32_e32 v230, v83, v194, vcc
	v_cndmask_b32_e64 v231, v83, v195, s[92:93]
	v_max3_f32 v200, v200, v201, v202
	v_max3_f32 v203, v203, v204, v205
	v_max3_f32 v206, v206, v207, v208
	v_max3_f32 v209, v209, v210, v211
	v_max3_f32 v212, v212, v213, v214
	v_max3_f32 v215, v215, v216, v217
	v_max3_f32 v218, v218, v219, v220
	v_max3_f32 v221, v221, v222, v223
	v_max3_f32 v224, v224, v225, v226
	v_max3_f32 v227, v227, v228, v229
	v_max_f32_e32 v230, v230, v231
	v_max3_f32 v200, v200, v203, v206
	v_max3_f32 v209, v209, v212, v215
	v_max3_f32 v218, v218, v221, v224
	v_max_f32_e32 v227, v227, v230
	v_max3_f32 v200, v200, v209, v218
	v_max_f32_e32 v200, v200, v227
	v_mov_b32_e32 v82, v200
	s_branch .Lswa_tdone_1

; template <int DH, int MODE>
; __device__ void attn_item(const Params& p, int layer, int b, int blk, int head, char* smem) {
;     ...
;       if (MODE == 0) {
;         const int kjb = kj0 + half * 32;
;         float tmax = -1e30f;
; #pragma unroll
;         for (int c = 0; c < 8; ++c) {
;           float4 v = s4[c];
;           float e[4] = {v.x, v.y, v.z, v.w};
; #pragma unroll
;           for (int k = 0; k < 4; ++k) {
;             int kj = kjb + c * 4 + k;
;             bool valid = (kj > row) && (kj <= row + 128);
;             tmax = valid ? fmaxf(tmax, e[k]) : tmax;
;           }
;         }
;         tmax = fmaxf(tmax, __shfl_xor(tmax, 1));
.LBB0_1129:
	s_or_b64 exec, exec, s[8:9]
	s_add_i32 s82, s82, 1
	s_min_i32 s8, s82, s80
	s_add_i32 s8, s8, s79
	s_lshl_b32 s8, s8, 6
	s_add_i32 s8, s8, s81
	s_ashr_i32 s9, s8, 31
	s_add_u32 s8, s8, s77
	s_addc_u32 s9, s9, 0
	s_waitcnt lgkmcnt(0)
	s_barrier
	ds_write_b16 v96, v48
	ds_write_b16_d16_hi v96, v48 offset:64
	ds_write_b16 v96, v49 offset:128
	ds_write_b16_d16_hi v96, v49 offset:192
	ds_write_b16 v96, v50 offset:256
	ds_write_b16_d16_hi v96, v50 offset:320
	ds_write_b16 v96, v51 offset:384
	ds_write_b16_d16_hi v96, v51 offset:448
	s_waitcnt vmcnt(0)
	ds_write_b16 v96, v52 offset:2048
	ds_write_b16_d16_hi v96, v52 offset:2112
	ds_write_b16 v96, v53 offset:2176
	ds_write_b16_d16_hi v96, v53 offset:2240
	ds_write_b16 v96, v54 offset:2304
	ds_write_b16_d16_hi v96, v54 offset:2368
	ds_write_b16 v96, v55 offset:2432
	ds_write_b16_d16_hi v96, v55 offset:2496
	v_lshl_add_u64 v[48:49], s[8:9], 0, v[66:67]
	v_mad_u64_u32 v[52:53], s[12:13], v48, s39, v[76:77]
	v_or_b32_e32 v48, s8, v72
	v_mad_i32_i24 v53, v49, s39, v53
	v_mad_u64_u32 v[54:55], s[12:13], v48, s39, v[78:79]
	v_add_co_u32_e32 v48, vcc, 0x4c000, v52
	v_mad_i32_i24 v55, s9, v160, v55
	s_nop 0
	v_addc_co_u32_e32 v49, vcc, 0, v53, vcc
	global_load_dwordx4 v[60:63], v[48:49], off
	s_nop 0
	global_load_dwordx4 v[48:51], v[54:55], off
	global_load_dwordx4 v[56:59], v[52:53], off
	s_nop 0
	global_load_dwordx4 v[52:55], v[54:55], off offset:64
	s_and_saveexec_b64 s[46:47], s[44:45]
	s_cbranch_execz .LBB0_1151
	v_or_b32_e32 v101, s10, v89
	s_setprio 1
	s_movk_i32 s91, 0x80
	ds_read_b128 v[164:167], v90 offset:16384
	ds_read_b128 v[168:171], v90 offset:16400
	ds_read_b128 v[172:175], v90 offset:16416
	ds_read_b128 v[176:179], v90 offset:16432
	ds_read_b128 v[180:183], v90 offset:16448
	ds_read_b128 v[184:187], v90 offset:16464
	ds_read_b128 v[188:191], v90 offset:16480
	ds_read_b128 v[192:195], v90 offset:16496
	v_sub_u32_e32 v102, v80, v101
	v_mov_b32_e32 v83, 0xf149f2ca
	v_add_u32_e32 v103, -31, v102
	v_cmp_gt_u32_e32 vcc, 0x61, v103
	s_cmp_eq_u64 vcc, exec
	s_cbranch_scc1 .Lswa_tfast_0
	v_mov_b32_e32 v161, v102
	v_add_u32_e32 v162, -1, v102
	v_add_u32_e32 v163, -2, v102
	v_cmp_gt_u32_e32 vcc, s91, v161
	v_cmp_gt_u32_e64 s[92:93], s91, v162
	v_cmp_gt_u32_e64 s[94:95], s91, v163
	s_waitcnt lgkmcnt(7)
	v_cndmask_b32_e32 v200, v83, v164, vcc
	v_cndmask_b32_e64 v201, v83, v165, s[92:93]
	v_cndmask_b32_e64 v202, v83, v166, s[94:95]
	v_add_u32_e32 v161, -3, v102
	v_add_u32_e32 v162, -4, v102
	v_add_u32_e32 v163, -5, v102
	v_cmp_gt_u32_e32 vcc, s91, v161
	v_cmp_gt_u32_e64 s[92:93], s91, v162
	v_cmp_gt_u32_e64 s[94:95], s91, v163
	s_waitcnt lgkmcnt(6)
	v_cndmask_b32_e32 v203, v83, v167, vcc
	v_cndmask_b32_e64 v204, v83, v168, s[92:93]
	v_cndmask_b32_e64 v205, v83, v169, s[94:95]
	v_add_u32_e32 v161, -6, v102
	v_add_u32_e32 v162, -7, v102
	v_add_u32_e32 v163, -8, v102
	v_cmp_gt_u32_e32 vcc, s91, v161
	v_cmp_gt_u32_e64 s[92:93], s91, v162
	v_cmp_gt_u32_e64 s[94:95], s91, v163
	s_waitcnt lgkmcnt(5)
	v_cndmask_b32_e32 v206, v83, v170, vcc
	v_cndmask_b32_e64 v207, v83, v171, s[92:93]
	v_cndmask_b32_e64 v208, v83, v172, s[94:95]
	v_add_u32_e32 v161, -9, v102
	v_add_u32_e32 v162, -10, v102
	v_add_u32_e32 v163, -11, v102
	v_cmp_gt_u32_e32 vcc, s91, v161
	v_cmp_gt_u32_e64 s[92:93], s91, v162
	v_cmp_gt_u32_e64 s[94:95], s91, v163
	v_cndmask_b32_e32 v209, v83, v173, vcc
	v_cndmask_b32_e64 v210, v83, v174, s[92:93]
	v_cndmask_b32_e64 v211, v83, v175, s[94:95]
	v_add_u32_e32 v161, -12, v102
	v_add_u32_e32 v162, -13, v102
	v_add_u32_e32 v163, -14, v102
	v_cmp_gt_u32_e32 vcc, s91, v161
	v_cmp_gt_u32_e64 s[92:93], s91, v162
	v_cmp_gt_u32_e64 s[94:95], s91, v163
	s_waitcnt lgkmcnt(4)
	v_cndmask_b32_e32 v212, v83, v176, vcc
	v_cndmask_b32_e64 v213, v83, v177, s[92:93]
	v_cndmask_b32_e64 v214, v83, v178, s[94:95]
	v_add_u32_e32 v161, -15, v102
	v_add_u32_e32 v162, -16, v102
	v_add_u32_e32 v163, 0xffffffef, v102
	v_cmp_gt_u32_e32 vcc, s91, v161
	v_cmp_gt_u32_e64 s[92:93], s91, v162
	v_cmp_gt_u32_e64 s[94:95], s91, v163
	s_waitcnt lgkmcnt(3)
	v_cndmask_b32_e32 v215, v83, v179, vcc
	v_cndmask_b32_e64 v216, v83, v180, s[92:93]
	v_cndmask_b32_e64 v217, v83, v181, s[94:95]
	v_add_u32_e32 v161, 0xffffffee, v102
	v_add_u32_e32 v162, 0xffffffed, v102
	v_add_u32_e32 v163, 0xffffffec, v102
	v_cmp_gt_u32_e32 vcc, s91, v161
	v_cmp_gt_u32_e64 s[92:93], s91, v162
	v_cmp_gt_u32_e64 s[94:95], s91, v163
	s_waitcnt lgkmcnt(2)
	v_cndmask_b32_e32 v218, v83, v182, vcc
	v_cndmask_b32_e64 v219, v83, v183, s[92:93]
	v_cndmask_b32_e64 v220, v83, v184, s[94:95]
	v_add_u32_e32 v161, 0xffffffeb, v102
	v_add_u32_e32 v162, 0xffffffea, v102
	v_add_u32_e32 v163, 0xffffffe9, v102
	v_cmp_gt_u32_e32 vcc, s91, v161
	v_cmp_gt_u32_e64 s[92:93], s91, v162
	v_cmp_gt_u32_e64 s[94:95], s91, v163
	v_cndmask_b32_e32 v221, v83, v185, vcc
	v_cndmask_b32_e64 v222, v83, v186, s[92:93]
	v_cndmask_b32_e64 v223, v83, v187, s[94:95]
	v_add_u32_e32 v161, 0xffffffe8, v102
	v_add_u32_e32 v162, 0xffffffe7, v102
	v_add_u32_e32 v163, 0xffffffe6, v102
	v_cmp_gt_u32_e32 vcc, s91, v161
	v_cmp_gt_u32_e64 s[92:93], s91, v162
	v_cmp_gt_u32_e64 s[94:95], s91, v163
	s_waitcnt lgkmcnt(1)
	v_cndmask_b32_e32 v224, v83, v188, vcc
	v_cndmask_b32_e64 v225, v83, v189, s[92:93]
	v_cndmask_b32_e64 v226, v83, v190, s[94:95]
	v_add_u32_e32 v161, 0xffffffe5, v102
	v_add_u32_e32 v162, 0xffffffe4, v102
	v_add_u32_e32 v163, 0xffffffe3, v102
	v_cmp_gt_u32_e32 vcc, s91, v161
	v_cmp_gt_u32_e64 s[92:93], s91, v162
	v_cmp_gt_u32_e64 s[94:95], s91, v163
	s_waitcnt lgkmcnt(0)
	v_cndmask_b32_e32 v227, v83, v191, vcc
	v_cndmask_b32_e64 v228, v83, v192, s[92:93]
	v_cndmask_b32_e64 v229, v83, v193, s[94:95]
	v_add_u32_e32 v161, 0xffffffe2, v102
	v_add_u32_e32 v162, 0xffffffe1, v102
	v_cmp_gt_u32_e32 vcc, s91, v161
	v_cmp_gt_u32_e64 s[92:93], s91, v162
	s_nop 0
	v_cndmask_b32_e32 v230, v83, v194, vcc
	v_cndmask_b32_e64 v231, v83, v195, s[92:93]
	v_max3_f32 v200, v200, v201, v202
	v_max3_f32 v203, v203, v204, v205
	v_max3_f32 v206, v206, v207, v208
	v_max3_f32 v209, v209, v210, v211
	v_max3_f32 v212, v212, v213, v214
	v_max3_f32 v215, v215, v216, v217
	v_max3_f32 v218, v218, v219, v220
	v_max3_f32 v221, v221, v222, v223
	v_max3_f32 v224, v224, v225, v226
	v_max3_f32 v227, v227, v228, v229
	v_max_f32_e32 v230, v230, v231
	v_max3_f32 v200, v200, v203, v206
	v_max3_f32 v209, v209, v212, v215
	v_max3_f32 v218, v218, v221, v224
	v_max_f32_e32 v227, v227, v230
	v_max3_f32 v200, v200, v209, v218
	v_max_f32_e32 v200, v200, v227
	v_mov_b32_e32 v82, v200
	s_branch .Lswa_tdone_0

; template <int DH, int MODE>
; __device__ void attn_item(const Params& p, int layer, int b, int blk, int head, char* smem) {
;     ...
;         tmax = fmaxf(tmax, __shfl_xor(tmax, 1));
;         float m_new = fmaxf(m_run, tmax);
;         float alpha = __builtin_amdgcn_exp2f(m_run - m_new);
;         float psum = 0.f;
; #pragma unroll 2
;         for (int s8 = 0; s8 < 4; ++s8) {
;           float4 va = s4[2 * s8], vb = s4[2 * s8 + 1];
;           float e[8] = {va.x, va.y, va.z, va.w, vb.x, vb.y, vb.z, vb.w};
;           float pv[8];
; #pragma unroll
;           for (int k = 0; k < 8; ++k) {
;             int kj = kjb + s8 * 8 + k;
;             bool valid = (kj > row) && (kj <= row + 128);
;             float pe = valid ? __builtin_amdgcn_exp2f(e[k] - m_new) : 0.f;
;             pv[k] = pe;
;             psum += pe;
.Lswa_tdone_0:
	v_cmp_lt_i32_e32 vcc, v157, v158
	s_mov_b32 s83, 0
	v_mov_b32_e32 v103, 0
	v_cndmask_b32_e32 v83, v156, v157, vcc
	v_lshlrev_b32_e32 v83, 2, v83
	ds_bpermute_b32 v101, v83, v82
	v_mov_b32_e32 v102, v91
	s_waitcnt lgkmcnt(0)
	v_max3_f32 v82, v87, v82, v101
	v_mov_b32_e32 v101, v93
	s_setprio 1
	s_movk_i32 s91, 0x80
	v_sub_u32_e32 v112, v80, v92
	v_add_u32_e32 v113, -31, v112
	v_cmp_gt_u32_e32 vcc, 0x61, v113
	s_cmp_eq_u64 vcc, exec
	s_cbranch_scc1 .Lswa_pfast_0
	v_sub_f32_e32 v164, v164, v82
	v_sub_f32_e32 v165, v165, v82
	v_sub_f32_e32 v166, v166, v82
	v_exp_f32_e32 v164, v164
	v_exp_f32_e32 v165, v165
	v_exp_f32_e32 v166, v166
	v_mov_b32_e32 v196, v112
	v_add_u32_e32 v197, -1, v112
	v_add_u32_e32 v198, -2, v112
	v_cmp_gt_u32_e32 vcc, s91, v196
	v_cmp_gt_u32_e64 s[92:93], s91, v197
	v_cmp_gt_u32_e64 s[94:95], s91, v198
	v_cndmask_b32_e32 v164, 0, v164, vcc
	v_cndmask_b32_e64 v165, 0, v165, s[92:93]
	v_cndmask_b32_e64 v166, 0, v166, s[94:95]
	v_add_f32_e32 v103, v103, v164
	v_add_f32_e32 v103, v103, v165
	v_add_f32_e32 v103, v103, v166
	v_sub_f32_e32 v167, v167, v82
	v_sub_f32_e32 v168, v168, v82
	v_sub_f32_e32 v169, v169, v82
	v_exp_f32_e32 v167, v167
	v_exp_f32_e32 v168, v168
	v_exp_f32_e32 v169, v169
	v_add_u32_e32 v196, -3, v112
	v_add_u32_e32 v197, -4, v112
	v_add_u32_e32 v198, -5, v112
	v_cmp_gt_u32_e32 vcc, s91, v196
	v_cmp_gt_u32_e64 s[92:93], s91, v197
	v_cmp_gt_u32_e64 s[94:95], s91, v198
	v_cndmask_b32_e32 v167, 0, v167, vcc
	v_cndmask_b32_e64 v168, 0, v168, s[92:93]
	v_cndmask_b32_e64 v169, 0, v169, s[94:95]
	v_add_f32_e32 v103, v103, v167
	v_add_f32_e32 v103, v103, v168
	v_add_f32_e32 v103, v103, v169
	v_sub_f32_e32 v170, v170, v82
	v_sub_f32_e32 v171, v171, v82
	v_sub_f32_e32 v172, v172, v82
	v_exp_f32_e32 v170, v170
	v_exp_f32_e32 v171, v171
	v_exp_f32_e32 v172, v172
	v_add_u32_e32 v196, -6, v112
	v_add_u32_e32 v197, -7, v112
	v_add_u32_e32 v198, -8, v112
	v_cmp_gt_u32_e32 vcc, s91, v196
	v_cmp_gt_u32_e64 s[92:93], s91, v197
	v_cmp_gt_u32_e64 s[94:95], s91, v198
	v_cndmask_b32_e32 v170, 0, v170, vcc
	v_cndmask_b32_e64 v171, 0, v171, s[92:93]
	v_cndmask_b32_e64 v172, 0, v172, s[94:95]
	v_add_f32_e32 v103, v103, v170
	v_add_f32_e32 v103, v103, v171
	v_add_f32_e32 v103, v103, v172
	v_sub_f32_e32 v173, v173, v82
	v_sub_f32_e32 v174, v174, v82
	v_sub_f32_e32 v175, v175, v82
	v_exp_f32_e32 v173, v173
	v_exp_f32_e32 v174, v174
	v_exp_f32_e32 v175, v175
	v_add_u32_e32 v196, -9, v112
	v_add_u32_e32 v197, -10, v112
	v_add_u32_e32 v198, -11, v112
	v_cmp_gt_u32_e32 vcc, s91, v196
	v_cmp_gt_u32_e64 s[92:93], s91, v197
	v_cmp_gt_u32_e64 s[94:95], s91, v198
	v_cndmask_b32_e32 v173, 0, v173, vcc
	v_cndmask_b32_e64 v174, 0, v174, s[92:93]
	v_cndmask_b32_e64 v175, 0, v175, s[94:95]
	v_add_f32_e32 v103, v103, v173
	v_add_f32_e32 v103, v103, v174
	v_add_f32_e32 v103, v103, v175
	v_sub_f32_e32 v176, v176, v82
	v_sub_f32_e32 v177, v177, v82
	v_sub_f32_e32 v178, v178, v82
	v_exp_f32_e32 v176, v176
	v_exp_f32_e32 v177, v177
	v_exp_f32_e32 v178, v178
	v_add_u32_e32 v196, -12, v112
	v_add_u32_e32 v197, -13, v112
	v_add_u32_e32 v198, -14, v112
	v_cmp_gt_u32_e32 vcc, s91, v196
	v_cmp_gt_u32_e64 s[92:93], s91, v197
	v_cmp_gt_u32_e64 s[94:95], s91, v198
	v_cndmask_b32_e32 v176, 0, v176, vcc
	v_cndmask_b32_e64 v177, 0, v177, s[92:93]
	v_cndmask_b32_e64 v178, 0, v178, s[94:95]
	v_add_f32_e32 v103, v103, v176
	v_add_f32_e32 v103, v103, v177
	v_add_f32_e32 v103, v103, v178
	v_sub_f32_e32 v179, v179, v82
	v_sub_f32_e32 v180, v180, v82
	v_sub_f32_e32 v181, v181, v82
	v_exp_f32_e32 v179, v179
	v_exp_f32_e32 v180, v180
	v_exp_f32_e32 v181, v181
	v_add_u32_e32 v196, -15, v112
	v_add_u32_e32 v197, -16, v112
	v_add_u32_e32 v198, 0xffffffef, v112
	v_cmp_gt_u32_e32 vcc, s91, v196
	v_cmp_gt_u32_e64 s[92:93], s91, v197
	v_cmp_gt_u32_e64 s[94:95], s91, v198
	v_cndmask_b32_e32 v179, 0, v179, vcc
; __device__ __forceinline__ unsigned pack2(float a, float b) { return (unsigned)f2bf(a) | ((unsigned)f2bf(b) << 16); }
; template <int DH, int MODE>
; __device__ void attn_item(const Params& p, int layer, int b, int blk, int head, char* smem) {
;     ...
; #pragma unroll 2
;         for (int s8 = 0; s8 < 4; ++s8) {
;           float4 va = s4[2 * s8], vb = s4[2 * s8 + 1];
;           float e[8] = {va.x, va.y, va.z, va.w, vb.x, vb.y, vb.z, vb.w};
;           float pv[8];
; #pragma unroll
;           for (int k = 0; k < 8; ++k) {
;             int kj = kjb + s8 * 8 + k;
;             bool valid = (kj > row) && (kj <= row + 128);
;             float pe = valid ? __builtin_amdgcn_exp2f(e[k] - m_new) : 0.f;
;             pv[k] = pe;
;             psum += pe;
;           }
;           uint4 ov;
;           ov.x = pack2(pv[0], pv[1]); ov.y = pack2(pv[2], pv[3]);
;           ov.z = pack2(pv[4], pv[5]); ov.w = pack2(pv[6], pv[7]);
;           *reinterpret_cast<uint4*>(prow + s8 * 16) = ov;
;         }
	v_cndmask_b32_e64 v180, 0, v180, s[92:93]
	v_cndmask_b32_e64 v181, 0, v181, s[94:95]
	v_add_f32_e32 v103, v103, v179
	v_add_f32_e32 v103, v103, v180
	v_add_f32_e32 v103, v103, v181
	v_sub_f32_e32 v182, v182, v82
	v_sub_f32_e32 v183, v183, v82
	v_sub_f32_e32 v184, v184, v82
	v_exp_f32_e32 v182, v182
	v_exp_f32_e32 v183, v183
	v_exp_f32_e32 v184, v184
	v_add_u32_e32 v196, 0xffffffee, v112
	v_add_u32_e32 v197, 0xffffffed, v112
	v_add_u32_e32 v198, 0xffffffec, v112
	v_cmp_gt_u32_e32 vcc, s91, v196
	v_cmp_gt_u32_e64 s[92:93], s91, v197
	v_cmp_gt_u32_e64 s[94:95], s91, v198
	v_cndmask_b32_e32 v182, 0, v182, vcc
	v_cndmask_b32_e64 v183, 0, v183, s[92:93]
	v_cndmask_b32_e64 v184, 0, v184, s[94:95]
	v_add_f32_e32 v103, v103, v182
	v_add_f32_e32 v103, v103, v183
	v_add_f32_e32 v103, v103, v184
	v_sub_f32_e32 v185, v185, v82
	v_sub_f32_e32 v186, v186, v82
	v_sub_f32_e32 v187, v187, v82
	v_exp_f32_e32 v185, v185
	v_exp_f32_e32 v186, v186
	v_exp_f32_e32 v187, v187
	v_add_u32_e32 v196, 0xffffffeb, v112
	v_add_u32_e32 v197, 0xffffffea, v112
	v_add_u32_e32 v198, 0xffffffe9, v112
	v_cmp_gt_u32_e32 vcc, s91, v196
	v_cmp_gt_u32_e64 s[92:93], s91, v197
	v_cmp_gt_u32_e64 s[94:95], s91, v198
	v_cndmask_b32_e32 v185, 0, v185, vcc
	v_cndmask_b32_e64 v186, 0, v186, s[92:93]
	v_cndmask_b32_e64 v187, 0, v187, s[94:95]
	v_add_f32_e32 v103, v103, v185
	v_add_f32_e32 v103, v103, v186
	v_add_f32_e32 v103, v103, v187
	v_sub_f32_e32 v188, v188, v82
	v_sub_f32_e32 v189, v189, v82
	v_sub_f32_e32 v190, v190, v82
	v_exp_f32_e32 v188, v188
	v_exp_f32_e32 v189, v189
	v_exp_f32_e32 v190, v190
	v_add_u32_e32 v196, 0xffffffe8, v112
	v_add_u32_e32 v197, 0xffffffe7, v112
	v_add_u32_e32 v198, 0xffffffe6, v112
	v_cmp_gt_u32_e32 vcc, s91, v196
	v_cmp_gt_u32_e64 s[92:93], s91, v197
	v_cmp_gt_u32_e64 s[94:95], s91, v198
	v_cndmask_b32_e32 v188, 0, v188, vcc
	v_cndmask_b32_e64 v189, 0, v189, s[92:93]
	v_cndmask_b32_e64 v190, 0, v190, s[94:95]
	v_add_f32_e32 v103, v103, v188
	v_add_f32_e32 v103, v103, v189
	v_add_f32_e32 v103, v103, v190
	v_sub_f32_e32 v191, v191, v82
	v_sub_f32_e32 v192, v192, v82
	v_sub_f32_e32 v193, v193, v82
	v_exp_f32_e32 v191, v191
	v_exp_f32_e32 v192, v192
	v_exp_f32_e32 v193, v193
	v_add_u32_e32 v196, 0xffffffe5, v112
	v_add_u32_e32 v197, 0xffffffe4, v112
	v_add_u32_e32 v198, 0xffffffe3, v112
	v_cmp_gt_u32_e32 vcc, s91, v196
	v_cmp_gt_u32_e64 s[92:93], s91, v197
	v_cmp_gt_u32_e64 s[94:95], s91, v198
	v_cndmask_b32_e32 v191, 0, v191, vcc
	v_cndmask_b32_e64 v192, 0, v192, s[92:93]
	v_cndmask_b32_e64 v193, 0, v193, s[94:95]
	v_add_f32_e32 v103, v103, v191
	v_add_f32_e32 v103, v103, v192
	v_add_f32_e32 v103, v103, v193
	v_sub_f32_e32 v194, v194, v82
	v_sub_f32_e32 v195, v195, v82
	v_exp_f32_e32 v194, v194
	v_exp_f32_e32 v195, v195
	v_add_u32_e32 v196, 0xffffffe2, v112
	v_add_u32_e32 v197, 0xffffffe1, v112
	v_cmp_gt_u32_e32 vcc, s91, v196
	v_cmp_gt_u32_e64 s[92:93], s91, v197
	s_nop 0
	v_cndmask_b32_e32 v194, 0, v194, vcc
	v_cndmask_b32_e64 v195, 0, v195, s[92:93]
	v_add_f32_e32 v103, v103, v194
	v_add_f32_e32 v103, v103, v195
	v_cvt_pk_bf16_f32 v104, v164, v165
	v_cvt_pk_bf16_f32 v105, v166, v167
	v_cvt_pk_bf16_f32 v106, v168, v169
	v_cvt_pk_bf16_f32 v107, v170, v171
	ds_write_b128 v101, v[104:107]
	s_nop 0
	v_cvt_pk_bf16_f32 v104, v172, v173
	v_cvt_pk_bf16_f32 v105, v174, v175
	v_cvt_pk_bf16_f32 v106, v176, v177
	v_cvt_pk_bf16_f32 v107, v178, v179
	ds_write_b128 v101, v[104:107] offset:16
	s_nop 0
	v_cvt_pk_bf16_f32 v104, v180, v181
	v_cvt_pk_bf16_f32 v105, v182, v183
	v_cvt_pk_bf16_f32 v106, v184, v185
	v_cvt_pk_bf16_f32 v107, v186, v187
	ds_write_b128 v101, v[104:107] offset:32
	s_nop 0
	v_cvt_pk_bf16_f32 v104, v188, v189
	v_cvt_pk_bf16_f32 v105, v190, v191
	v_cvt_pk_bf16_f32 v106, v192, v193
	v_cvt_pk_bf16_f32 v107, v194, v195
	ds_write_b128 v101, v[104:107] offset:48
	s_branch .Lswa_pdone_0

; __device__ __forceinline__ unsigned pack2(float a, float b) { return (unsigned)f2bf(a) | ((unsigned)f2bf(b) << 16); }
; template <int DH, int MODE>
; __device__ void attn_item(const Params& p, int layer, int b, int blk, int head, char* smem) {
;     ...
;         float alpha = __builtin_amdgcn_exp2f(m_run - m_new);
;         float psum = 0.f;
; #pragma unroll 2
;         for (int s8 = 0; s8 < 4; ++s8) {
;           float4 va = s4[2 * s8], vb = s4[2 * s8 + 1];
;           float e[8] = {va.x, va.y, va.z, va.w, vb.x, vb.y, vb.z, vb.w};
;           float pv[8];
; #pragma unroll
;           for (int k = 0; k < 8; ++k) {
;             int kj = kjb + s8 * 8 + k;
;             bool valid = (kj > row) && (kj <= row + 128);
;             float pe = valid ? __builtin_amdgcn_exp2f(e[k] - m_new) : 0.f;
;             pv[k] = pe;
;             psum += pe;
;           }
;           uint4 ov;
;           ov.x = pack2(pv[0], pv[1]); ov.y = pack2(pv[2], pv[3]);
;           ov.z = pack2(pv[4], pv[5]); ov.w = pack2(pv[6], pv[7]);
;           *reinterpret_cast<uint4*>(prow + s8 * 16) = ov;
;         }
;         psum += __shfl_xor(psum, 1);
;         l_run = l_run * alpha + psum;
;         m_run = m_new;
;         if (half == 0) alpha_s[row] = alpha;
.Lswa_pdone_0:
	s_setprio 0
	v_sub_f32_e32 v101, v87, v82
	ds_bpermute_b32 v87, v83, v103
	v_exp_f32_e32 v83, v101
	s_and_saveexec_b64 s[8:9], s[6:7]
	ds_write_b32 v97, v83 offset:8192
	s_or_b64 exec, exec, s[8:9]
	s_waitcnt lgkmcnt(0)
	v_add_f32_e32 v101, v103, v87
	v_fmac_f32_e32 v101, v88, v83
	v_mov_b32_e32 v87, v82
	v_mov_b32_e32 v88, v101
